# k11 + mLSTM scan output waves: operand LDS reads issued up to 15 deep ahead of the MFMAs (ring of 18 slots in dead registers), denominator bpermutes batched
# speedup vs baseline: 1.0047x; 1.0047x over previous
.LBB0_1927:
	v_add_u32_e32 v2, 0x2000, v151
	ds_read2_b64 v[166:169], v2 offset0:128 offset1:132
	ds_read_b128 v[170:173], v127
	ds_read_b128 v[174:177], v127 offset:1024
	ds_read_b128 v[178:181], v127 offset:2048
	ds_read2_b64 v[182:185], v2 offset0:136 offset1:140
	ds_read_b128 v[186:189], v127 offset:3072
	ds_read_b128 v[190:193], v127 offset:4096
	ds_read_b128 v[194:197], v127 offset:5120
	ds_read2_b64 v[198:201], v2 offset0:144 offset1:148
	ds_read_b128 v[202:205], v127 offset:6144
	ds_read_b128 v[206:209], v127 offset:7168
	ds_read_b128 v[210:213], v127 offset:8192
	ds_read2_b64 v[214:217], v2 offset0:152 offset1:156
	ds_read_b128 v[218:221], v127 offset:9216
	ds_read_b128 v[222:225], v127 offset:10240
	s_cmp_gt_u32 s82, 3
	s_cselect_b32 s28, 0x47, 3
	s_add_i32 s28, s28, s81
	s_add_i32 s40, s28, 1
	s_and_b64 s[28:29], s[44:45], exec
	s_cselect_b32 s28, s82, s40
	s_lshl_b32 s29, s28, 6
	s_add_i32 s29, s48, s29
	s_add_i32 s40, s49, s28
	s_cmp_gt_i32 s28, 3
	s_cselect_b32 s28, s40, s29
	s_cselect_b32 s40, 16, 10
	s_ashr_i32 s29, s28, 31
	s_add_u32 s28, s28, s77
	s_addc_u32 s29, s29, 0
	s_lshl_b64 s[28:29], s[28:29], 12
	s_add_u32 s28, s79, s28
	s_addc_u32 s29, s80, s29
	s_waitcnt lgkmcnt(13)
	v_mfma_f32_16x16x32_bf16 v[158:161], v[166:169], v[170:173], 0
	ds_read_b128 v[226:229], v127 offset:11264
	ds_read2_b64 v[230:233], v2 offset0:160 offset1:164
	s_waitcnt lgkmcnt(14)
	v_mfma_f32_16x16x32_bf16 v[162:165], v[166:169], v[174:177], 0
	ds_read_b128 v[234:237], v127 offset:12288
	s_waitcnt lgkmcnt(14)
	v_mfma_f32_16x16x32_bf16 v[154:157], v[166:169], v[178:181], 0
	ds_read_b128 v[170:173], v127 offset:13312
	s_waitcnt lgkmcnt(13)
	v_mfma_f32_16x16x32_bf16 v[158:161], v[182:185], v[186:189], v[158:161]
	ds_read_b128 v[174:177], v127 offset:14336
	ds_read2_b64 v[166:169], v2 offset0:168 offset1:172
	s_waitcnt lgkmcnt(14)
	v_mfma_f32_16x16x32_bf16 v[162:165], v[182:185], v[190:193], v[162:165]
	ds_read_b128 v[178:181], v127 offset:15360
	s_waitcnt lgkmcnt(14)
	v_mfma_f32_16x16x32_bf16 v[154:157], v[182:185], v[194:197], v[154:157]
	ds_read_b128 v[186:189], v127 offset:16384
	s_waitcnt lgkmcnt(13)
	v_mfma_f32_16x16x32_bf16 v[158:161], v[198:201], v[202:205], v[158:161]
	ds_read_b128 v[190:193], v127 offset:17408
	ds_read2_b64 v[182:185], v2 offset0:176 offset1:180
	s_waitcnt lgkmcnt(14)
	v_mfma_f32_16x16x32_bf16 v[162:165], v[198:201], v[206:209], v[162:165]
	ds_read_b128 v[194:197], v127 offset:18432
	s_waitcnt lgkmcnt(14)
	v_mfma_f32_16x16x32_bf16 v[154:157], v[198:201], v[210:213], v[154:157]
	ds_read_b128 v[202:205], v127 offset:19456
	s_waitcnt lgkmcnt(13)
	v_mfma_f32_16x16x32_bf16 v[158:161], v[214:217], v[218:221], v[158:161]
	ds_read_b128 v[206:209], v127 offset:20480
	ds_read2_b64 v[198:201], v2 offset0:184 offset1:188
	s_waitcnt lgkmcnt(14)
	v_mfma_f32_16x16x32_bf16 v[162:165], v[214:217], v[222:225], v[162:165]
	ds_read_b128 v[210:213], v127 offset:21504
	s_waitcnt lgkmcnt(14)
	v_mfma_f32_16x16x32_bf16 v[154:157], v[214:217], v[226:229], v[154:157]
	ds_read_b128 v[218:221], v127 offset:22528
	s_waitcnt lgkmcnt(13)
	v_mfma_f32_16x16x32_bf16 v[158:161], v[230:233], v[234:237], v[158:161]
	ds_read_b128 v[222:225], v127 offset:23552
	ds_read_b128 v[214:217], v128
	s_waitcnt lgkmcnt(14)
	v_mfma_f32_16x16x32_bf16 v[162:165], v[230:233], v[170:173], v[162:165]
	ds_read_b128 v[226:229], v128 offset:64
	s_waitcnt lgkmcnt(14)
	v_mfma_f32_16x16x32_bf16 v[154:157], v[230:233], v[174:177], v[154:157]
	ds_read_b128 v[234:237], v143
	s_waitcnt lgkmcnt(13)
	v_mfma_f32_16x16x32_bf16 v[158:161], v[166:169], v[178:181], v[158:161]
	ds_read_b128 v[170:173], v143 offset:2304
	ds_read_b128 v[230:233], v143 offset:64
	s_waitcnt lgkmcnt(14)
	v_mfma_f32_16x16x32_bf16 v[162:165], v[166:169], v[186:189], v[162:165]
	ds_read_b128 v[174:177], v143 offset:2368
	s_waitcnt lgkmcnt(14)
	v_mfma_f32_16x16x32_bf16 v[154:157], v[166:169], v[190:193], v[154:157]
	ds_read_b128 v[178:181], v130
	s_waitcnt lgkmcnt(13)
	v_mfma_f32_16x16x32_bf16 v[158:161], v[182:185], v[194:197], v[158:161]
	s_waitcnt lgkmcnt(12)
	v_mfma_f32_16x16x32_bf16 v[162:165], v[182:185], v[202:205], v[162:165]
	s_waitcnt lgkmcnt(11)
	v_mfma_f32_16x16x32_bf16 v[154:157], v[182:185], v[206:209], v[154:157]
	s_waitcnt lgkmcnt(9)
	v_mfma_f32_16x16x32_bf16 v[158:161], v[198:201], v[210:213], v[158:161]
	s_waitcnt lgkmcnt(8)
	v_mfma_f32_16x16x32_bf16 v[162:165], v[198:201], v[218:221], v[162:165]
	s_waitcnt lgkmcnt(7)
	v_mfma_f32_16x16x32_bf16 v[154:157], v[198:201], v[222:225], v[154:157]
	s_waitcnt lgkmcnt(6)
	v_mfma_f32_16x16x32_bf16 v[154:157], v[214:217], v[46:49], v[154:157]
	s_waitcnt lgkmcnt(5)
	v_mfma_f32_16x16x32_bf16 v[154:157], v[226:229], v[46:49], v[154:157]
	s_waitcnt lgkmcnt(4)
	v_mfma_f32_16x16x32_bf16 v[158:161], v[214:217], v[234:237], v[158:161]
	s_waitcnt lgkmcnt(3)
	v_mfma_f32_16x16x32_bf16 v[162:165], v[214:217], v[170:173], v[162:165]
	s_waitcnt lgkmcnt(2)
	v_mfma_f32_16x16x32_bf16 v[158:161], v[226:229], v[230:233], v[158:161]
	s_waitcnt lgkmcnt(1)
	v_mfma_f32_16x16x32_bf16 v[162:165], v[226:229], v[174:177], v[162:165]
	s_nop 0
	ds_bpermute_b32 v186, v152, v154
	ds_bpermute_b32 v187, v152, v155
	ds_bpermute_b32 v188, v152, v156
	ds_bpermute_b32 v189, v152, v157
	s_waitcnt lgkmcnt(4)
	v_max_f32_e32 v190, v178, v178
	v_max_f32_e32 v191, v179, v179
	v_max_f32_e32 v192, v180, v180
	v_max_f32_e32 v193, v181, v181
	v_lshl_or_b32 v2, v129, s40, v122
	v_lshl_add_u64 v[4:5], v[2:3], 2, s[28:29]
	s_waitcnt lgkmcnt(0)
	v_max_f32_e64 v186, |v186|, |v186|
	v_max_f32_e64 v187, |v187|, |v187|
	v_max_f32_e64 v188, |v188|, |v188|
	v_max_f32_e64 v189, |v189|, |v189|
	v_max_f32_e32 v186, v186, v190
	v_max_f32_e32 v187, v187, v191
	v_max_f32_e32 v188, v188, v192
	v_max_f32_e32 v189, v189, v193
	v_rcp_f32_e32 v166, v186
	v_rcp_f32_e32 v167, v187
	v_rcp_f32_e32 v168, v188
	v_rcp_f32_e32 v169, v189
	v_mul_f32_e32 v192, v158, v166
	v_mul_f32_e32 v193, v162, v166
	global_store_dword v[4:5], v192, off
	global_store_dword v[4:5], v193, off offset:64
	v_lshl_add_u32 v2, v131, s40, v122
	v_lshl_add_u64 v[4:5], v[2:3], 2, s[28:29]
	v_mul_f32_e32 v192, v159, v167
	v_mul_f32_e32 v193, v163, v167
	global_store_dword v[4:5], v192, off
	global_store_dword v[4:5], v193, off offset:64
	v_lshl_add_u32 v2, v132, s40, v122
	v_lshl_add_u64 v[4:5], v[2:3], 2, s[28:29]
	v_mul_f32_e32 v192, v160, v168
	v_mul_f32_e32 v193, v164, v168
	global_store_dword v[4:5], v192, off
	global_store_dword v[4:5], v193, off offset:64
	v_lshl_add_u32 v2, v133, s40, v122
	v_lshl_add_u64 v[4:5], v[2:3], 2, s[28:29]
	v_mul_f32_e32 v192, v161, v169
	v_mul_f32_e32 v2, v165, v169
	global_store_dword v[4:5], v192, off
	global_store_dword v[4:5], v2, off offset:64
	s_branch .LBB0_1911
